# nt (instead of sc1) on GEMM1 epilogue stores of late-consumed tiles (r_ssm, r_conv, silu(g_ssm)); rest as v42
# baseline (speedup 1.0000x reference)
.LBB0_166:
	s_lshl_b32 s17, s89, 8
	s_add_i32 s17, s17, s61
	v_or_b32_e32 v152, s17, v1
	s_cmp_gt_i32 s88, 1
	s_mov_b64 s[18:19], -1
	s_cbranch_scc0 .LBB0_181
	s_cmp_gt_u32 s88, 3
	s_cbranch_scc0 .LBB0_177
	s_cmp_gt_u32 s88, 11
	s_cbranch_scc0 .LBB0_174
	s_cmp_gt_u32 s88, 19
	s_cbranch_scc0 .LBB0_171
	s_cmp_lt_u32 s88, 24
	s_cselect_b64 s[18:19], -1, 0
	s_and_b64 s[18:19], s[18:19], exec
	s_movk_i32 s18, 0xffec
	s_cselect_b32 s21, s18, 0xffffffe8
	s_mov_b32 s18, 0x8600000
	s_cselect_b32 s18, s18, 0xa600000
	s_add_u32 s18, s78, s18
	s_addc_u32 s19, s79, 0
	s_add_i32 s21, s21, s88
	v_lshl_or_b32 v166, s21, 8, v159
	v_ashrrev_i32_e32 v153, 31, v152
	v_lshlrev_b64 v[154:155], 11, v[152:153]
	v_ashrrev_i32_e32 v167, 31, v166
	v_lshl_add_u64 v[168:169], s[18:19], 0, v[154:155]
	v_lshlrev_b64 v[166:167], 1, v[166:167]
	v_cvt_pk_bf16_f32 v154, v126, v127
	v_cvt_pk_bf16_f32 v155, v128, v129
	v_cvt_pk_bf16_f32 v156, v122, v123
	v_cvt_pk_bf16_f32 v157, v124, v125
	v_lshl_add_u64 v[168:169], v[168:169], 0, v[166:167]
	global_store_dwordx4 v[168:169], v[154:157], off nt
	s_nop 1
	v_cvt_pk_bf16_f32 v154, v110, v111
	v_cvt_pk_bf16_f32 v155, v112, v113
	v_cvt_pk_bf16_f32 v156, v106, v107
	v_cvt_pk_bf16_f32 v157, v108, v109
	global_store_dwordx4 v[168:169], v[154:157], off offset:256 nt
	s_nop 1
	v_or_b32_e32 v154, 16, v152
	v_ashrrev_i32_e32 v155, 31, v154
	v_lshlrev_b64 v[154:155], 11, v[154:155]
	v_lshl_add_u64 v[170:171], s[18:19], 0, v[154:155]
	v_cvt_pk_bf16_f32 v154, v118, v119
	v_cvt_pk_bf16_f32 v155, v120, v121
	v_cvt_pk_bf16_f32 v156, v114, v115
	v_cvt_pk_bf16_f32 v157, v116, v117
	v_lshl_add_u64 v[170:171], v[170:171], 0, v[166:167]
	global_store_dwordx4 v[170:171], v[154:157], off nt
	s_nop 1
	v_cvt_pk_bf16_f32 v154, v94, v95
	v_cvt_pk_bf16_f32 v155, v96, v97
	v_cvt_pk_bf16_f32 v156, v90, v91
	v_cvt_pk_bf16_f32 v157, v92, v93
	global_store_dwordx4 v[170:171], v[154:157], off offset:256 nt
	s_nop 1
	v_or_b32_e32 v154, 32, v152
	v_ashrrev_i32_e32 v155, 31, v154
	v_lshlrev_b64 v[154:155], 11, v[154:155]
	v_lshl_add_u64 v[170:171], s[18:19], 0, v[154:155]
	v_cvt_pk_bf16_f32 v154, v102, v103
	v_cvt_pk_bf16_f32 v155, v104, v105
	v_cvt_pk_bf16_f32 v156, v98, v99
	v_cvt_pk_bf16_f32 v157, v100, v101
	v_lshl_add_u64 v[170:171], v[170:171], 0, v[166:167]
	global_store_dwordx4 v[170:171], v[154:157], off nt
	s_nop 1
	v_cvt_pk_bf16_f32 v154, v78, v79
	v_cvt_pk_bf16_f32 v155, v80, v81
	v_cvt_pk_bf16_f32 v156, v74, v75
	v_cvt_pk_bf16_f32 v157, v76, v77
	global_store_dwordx4 v[170:171], v[154:157], off offset:256 nt
	s_nop 1
	v_or_b32_e32 v154, 48, v152
	v_ashrrev_i32_e32 v155, 31, v154
	v_lshlrev_b64 v[154:155], 11, v[154:155]
	v_lshl_add_u64 v[170:171], s[18:19], 0, v[154:155]
	v_cvt_pk_bf16_f32 v154, v86, v87
	v_cvt_pk_bf16_f32 v155, v88, v89
	v_cvt_pk_bf16_f32 v156, v82, v83
	v_cvt_pk_bf16_f32 v157, v84, v85
	v_lshl_add_u64 v[166:167], v[170:171], 0, v[166:167]
	global_store_dwordx4 v[166:167], v[154:157], off nt
	v_add_co_u32_e32 v170, vcc, s84, v168
	s_nop 0
	v_cvt_pk_bf16_f32 v154, v70, v71
	v_cvt_pk_bf16_f32 v155, v72, v73
	v_cvt_pk_bf16_f32 v156, v66, v67
	v_cvt_pk_bf16_f32 v157, v68, v69
	global_store_dwordx4 v[166:167], v[154:157], off offset:256 nt
	s_mov_b64 s[18:19], 0x40000
	v_addc_co_u32_e32 v171, vcc, 0, v169, vcc
	v_cvt_pk_bf16_f32 v154, v62, v63
	v_cvt_pk_bf16_f32 v155, v64, v65
	v_cvt_pk_bf16_f32 v156, v58, v59
	v_cvt_pk_bf16_f32 v157, v60, v61
	v_lshl_add_u64 v[166:167], v[168:169], 0, s[18:19]
	global_store_dwordx4 v[170:171], v[154:157], off nt
	v_add_co_u32_e32 v170, vcc, s85, v168
	s_nop 0
	v_cvt_pk_bf16_f32 v154, v46, v47
	v_cvt_pk_bf16_f32 v155, v48, v49
	v_cvt_pk_bf16_f32 v156, v42, v43
	v_cvt_pk_bf16_f32 v157, v44, v45
	global_store_dwordx4 v[166:167], v[154:157], off offset:256 nt
	s_mov_b64 s[18:19], 0x48000
	v_addc_co_u32_e32 v171, vcc, 0, v169, vcc
	v_cvt_pk_bf16_f32 v154, v54, v55
	v_cvt_pk_bf16_f32 v155, v56, v57
	v_cvt_pk_bf16_f32 v156, v50, v51
	v_cvt_pk_bf16_f32 v157, v52, v53
	v_lshl_add_u64 v[166:167], v[168:169], 0, s[18:19]
	global_store_dwordx4 v[170:171], v[154:157], off nt
	v_add_co_u32_e32 v170, vcc, s86, v168
	s_nop 0
	v_cvt_pk_bf16_f32 v154, v30, v31
	v_cvt_pk_bf16_f32 v155, v32, v33
	v_cvt_pk_bf16_f32 v156, v26, v27
	v_cvt_pk_bf16_f32 v157, v28, v29
	global_store_dwordx4 v[166:167], v[154:157], off offset:256 nt
	s_mov_b64 s[18:19], 0x50000
	v_addc_co_u32_e32 v171, vcc, 0, v169, vcc
	v_cvt_pk_bf16_f32 v154, v38, v39
	v_cvt_pk_bf16_f32 v155, v40, v41
	v_cvt_pk_bf16_f32 v156, v34, v35
	v_cvt_pk_bf16_f32 v157, v36, v37
	v_lshl_add_u64 v[166:167], v[168:169], 0, s[18:19]
	global_store_dwordx4 v[170:171], v[154:157], off nt
	s_mov_b64 s[18:19], 0x58000
	s_nop 0
	v_cvt_pk_bf16_f32 v154, v14, v15
	v_cvt_pk_bf16_f32 v155, v16, v17
	v_cvt_pk_bf16_f32 v156, v10, v11
	v_cvt_pk_bf16_f32 v157, v12, v13
	global_store_dwordx4 v[166:167], v[154:157], off offset:256 nt
	v_lshl_add_u64 v[166:167], v[168:169], 0, s[18:19]
	s_mov_b32 s18, 0x58000
	v_add_co_u32_e32 v168, vcc, s18, v168
	v_cvt_pk_bf16_f32 v154, v22, v23
	v_cvt_pk_bf16_f32 v155, v24, v25
	v_cvt_pk_bf16_f32 v156, v18, v19
	v_cvt_pk_bf16_f32 v157, v20, v21
	v_addc_co_u32_e32 v169, vcc, 0, v169, vcc
	global_store_dwordx4 v[168:169], v[154:157], off nt
	s_mov_b64 s[18:19], 0
	s_nop 0
	v_cvt_pk_bf16_f32 v154, v6, v7
	v_cvt_pk_bf16_f32 v155, v8, v9
	v_cvt_pk_bf16_f32 v156, v2, v3
	v_cvt_pk_bf16_f32 v157, v4, v5
	global_store_dwordx4 v[166:167], v[154:157], off offset:256 nt

.LBB0_177:
	s_andn2_b64 vcc, exec, s[18:19]
	s_cbranch_vccnz .LBB0_179
	v_mul_f32_e32 v138, 0xbfb8aa3b, v126
	v_ashrrev_i32_e32 v153, 31, v152
	v_exp_f32_e32 v151, v138
	v_lshlrev_b64 v[154:155], 10, v[152:153]
	v_mul_f32_e32 v153, 0xbfb8aa3b, v127
	v_exp_f32_e32 v153, v153
	v_mul_f32_e32 v156, 0xbfb8aa3b, v128
	v_exp_f32_e32 v166, v156
	v_add_f32_e32 v151, 1.0, v151
	v_rcp_f32_e32 v156, v151
	v_add_f32_e32 v151, 1.0, v153
	v_mul_f32_e32 v153, 0xbfb8aa3b, v129
	v_rcp_f32_e32 v157, v151
	v_add_f32_e32 v151, 1.0, v166
	v_exp_f32_e32 v153, v153
	v_mul_f32_e32 v166, 0xbfb8aa3b, v122
	v_exp_f32_e32 v168, v166
	v_rcp_f32_e32 v166, v151
	v_add_f32_e32 v151, 1.0, v153
	v_rcp_f32_e32 v167, v151
	v_add_f32_e32 v151, 1.0, v168
	v_rcp_f32_e32 v168, v151
	v_mul_f32_e32 v151, 0xbfb8aa3b, v123
	v_mul_f32_e32 v153, 0xbfb8aa3b, v124
	v_exp_f32_e32 v151, v151
	v_exp_f32_e32 v153, v153
	v_mul_f32_e32 v169, 0xbfb8aa3b, v125
	v_exp_f32_e32 v169, v169
	v_add_f32_e32 v151, 1.0, v151
	v_add_f32_e32 v153, 1.0, v153
	v_rcp_f32_e32 v170, v153
	v_add_f32_e32 v153, 1.0, v169
	v_rcp_f32_e32 v169, v151
	v_mul_f32_e32 v151, 0xbfb8aa3b, v110
	v_exp_f32_e32 v151, v151
	v_lshl_add_u32 v138, s88, 8, v161
	v_rcp_f32_e32 v171, v153
	v_pk_mul_f32 v[156:157], v[126:127], v[156:157]
	v_pk_mul_f32 v[172:173], v[128:129], v[166:167]
	v_cvt_pk_bf16_f32 v166, v156, v157
	v_lshlrev_b64 v[156:157], 1, v[138:139]
	v_add_f32_e32 v138, 1.0, v151
	v_mul_f32_e32 v151, 0xbfb8aa3b, v111
	v_exp_f32_e32 v151, v151
	v_mul_f32_e32 v153, 0xbfb8aa3b, v112
	v_exp_f32_e32 v153, v153
	v_pk_mul_f32 v[170:171], v[124:125], v[170:171]
	v_pk_mul_f32 v[168:169], v[122:123], v[168:169]
	v_lshl_add_u64 v[154:155], s[8:9], 0, v[154:155]
	v_cvt_pk_bf16_f32 v167, v172, v173
	v_cvt_pk_bf16_f32 v168, v168, v169
	v_cvt_pk_bf16_f32 v169, v170, v171
	v_lshl_add_u64 v[154:155], v[154:155], 0, v[156:157]
	global_store_dwordx4 v[154:155], v[166:169], off nt
	s_mov_b64 s[18:19], 0x20000
	s_nop 0
	v_rcp_f32_e32 v166, v138
	v_add_f32_e32 v138, 1.0, v151
	v_mul_f32_e32 v151, 0xbfb8aa3b, v113
	v_rcp_f32_e32 v167, v138
	v_add_f32_e32 v138, 1.0, v153
	v_exp_f32_e32 v151, v151
	v_mul_f32_e32 v153, 0xbfb8aa3b, v106
	v_exp_f32_e32 v153, v153
	v_rcp_f32_e32 v168, v138
	v_add_f32_e32 v138, 1.0, v151
	v_rcp_f32_e32 v169, v138
	v_add_f32_e32 v138, 1.0, v153
	v_mul_f32_e32 v151, 0xbfb8aa3b, v108
	v_rcp_f32_e32 v170, v138
	v_mul_f32_e32 v138, 0xbfb8aa3b, v107
	v_exp_f32_e32 v151, v151
	v_mul_f32_e32 v153, 0xbfb8aa3b, v109
	v_exp_f32_e32 v138, v138
	v_exp_f32_e32 v153, v153
	v_add_f32_e32 v151, 1.0, v151
	v_rcp_f32_e32 v172, v151
	v_add_f32_e32 v138, 1.0, v138
	v_add_f32_e32 v151, 1.0, v153
	v_rcp_f32_e32 v173, v151
	v_rcp_f32_e32 v171, v138
	v_mul_f32_e32 v138, 0xbfb8aa3b, v118
	v_exp_f32_e32 v138, v138
	v_mul_f32_e32 v151, 0xbfb8aa3b, v119
	v_pk_mul_f32 v[168:169], v[112:113], v[168:169]
	v_pk_mul_f32 v[166:167], v[110:111], v[166:167]
	v_pk_mul_f32 v[172:173], v[108:109], v[172:173]
	v_pk_mul_f32 v[170:171], v[106:107], v[170:171]
	v_exp_f32_e32 v151, v151
	v_mul_f32_e32 v153, 0xbfb8aa3b, v120
	v_cvt_pk_bf16_f32 v166, v166, v167
	v_cvt_pk_bf16_f32 v167, v168, v169
	v_cvt_pk_bf16_f32 v168, v170, v171
	v_cvt_pk_bf16_f32 v169, v172, v173
	v_exp_f32_e32 v153, v153
	global_store_dwordx4 v[154:155], v[166:169], off offset:256 nt
	v_add_f32_e32 v138, 1.0, v138
	s_nop 0
	v_or_b32_e32 v166, 16, v152
	v_ashrrev_i32_e32 v167, 31, v166
	v_lshlrev_b64 v[170:171], 10, v[166:167]
	v_rcp_f32_e32 v166, v138
	v_add_f32_e32 v138, 1.0, v151
	v_mul_f32_e32 v151, 0xbfb8aa3b, v121
	v_rcp_f32_e32 v167, v138
	v_add_f32_e32 v138, 1.0, v153
	v_exp_f32_e32 v151, v151
	v_mul_f32_e32 v153, 0xbfb8aa3b, v114
	v_exp_f32_e32 v153, v153
	v_rcp_f32_e32 v168, v138
	v_add_f32_e32 v138, 1.0, v151
	v_rcp_f32_e32 v169, v138
	v_add_f32_e32 v138, 1.0, v153
	v_mul_f32_e32 v151, 0xbfb8aa3b, v116
	v_rcp_f32_e32 v172, v138
	v_mul_f32_e32 v138, 0xbfb8aa3b, v115
	v_exp_f32_e32 v151, v151
	v_mul_f32_e32 v153, 0xbfb8aa3b, v117
	v_exp_f32_e32 v138, v138
	v_exp_f32_e32 v153, v153
	v_add_f32_e32 v151, 1.0, v151
	v_rcp_f32_e32 v174, v151
	v_add_f32_e32 v138, 1.0, v138
	v_add_f32_e32 v151, 1.0, v153
	v_rcp_f32_e32 v175, v151
	v_rcp_f32_e32 v173, v138
	v_mul_f32_e32 v138, 0xbfb8aa3b, v94
	v_exp_f32_e32 v138, v138
	v_mul_f32_e32 v151, 0xbfb8aa3b, v95
	v_exp_f32_e32 v151, v151
	v_mul_f32_e32 v153, 0xbfb8aa3b, v96
	v_exp_f32_e32 v153, v153
	v_pk_mul_f32 v[168:169], v[120:121], v[168:169]
	v_pk_mul_f32 v[166:167], v[118:119], v[166:167]
	v_pk_mul_f32 v[174:175], v[116:117], v[174:175]
	v_pk_mul_f32 v[172:173], v[114:115], v[172:173]
	v_lshl_add_u64 v[170:171], s[8:9], 0, v[170:171]
	v_cvt_pk_bf16_f32 v166, v166, v167
	v_cvt_pk_bf16_f32 v167, v168, v169
	v_cvt_pk_bf16_f32 v168, v172, v173
	v_cvt_pk_bf16_f32 v169, v174, v175
	v_lshl_add_u64 v[170:171], v[170:171], 0, v[156:157]
	v_add_f32_e32 v138, 1.0, v138
	global_store_dwordx4 v[170:171], v[166:169], off nt
	s_nop 1
	v_rcp_f32_e32 v166, v138
	v_add_f32_e32 v138, 1.0, v151
	v_mul_f32_e32 v151, 0xbfb8aa3b, v97
	v_rcp_f32_e32 v167, v138
	v_add_f32_e32 v138, 1.0, v153
	v_exp_f32_e32 v151, v151
	v_mul_f32_e32 v153, 0xbfb8aa3b, v90
	v_exp_f32_e32 v153, v153
	v_rcp_f32_e32 v168, v138
	v_add_f32_e32 v138, 1.0, v151
	v_rcp_f32_e32 v169, v138
	v_add_f32_e32 v138, 1.0, v153
	v_mul_f32_e32 v151, 0xbfb8aa3b, v92
	v_rcp_f32_e32 v172, v138
	v_mul_f32_e32 v138, 0xbfb8aa3b, v91
	v_exp_f32_e32 v151, v151
	v_mul_f32_e32 v153, 0xbfb8aa3b, v93
	v_exp_f32_e32 v138, v138
	v_exp_f32_e32 v153, v153
	v_add_f32_e32 v151, 1.0, v151
	v_rcp_f32_e32 v174, v151
	v_add_f32_e32 v138, 1.0, v138
	v_add_f32_e32 v151, 1.0, v153
	v_rcp_f32_e32 v175, v151
	v_rcp_f32_e32 v173, v138
	v_mul_f32_e32 v138, 0xbfb8aa3b, v102
	v_exp_f32_e32 v138, v138
	v_mul_f32_e32 v151, 0xbfb8aa3b, v103
	v_pk_mul_f32 v[168:169], v[96:97], v[168:169]
	v_pk_mul_f32 v[166:167], v[94:95], v[166:167]
	v_pk_mul_f32 v[174:175], v[92:93], v[174:175]
	v_pk_mul_f32 v[172:173], v[90:91], v[172:173]
	v_exp_f32_e32 v151, v151
	v_mul_f32_e32 v153, 0xbfb8aa3b, v104
	v_cvt_pk_bf16_f32 v166, v166, v167
	v_cvt_pk_bf16_f32 v167, v168, v169
	v_cvt_pk_bf16_f32 v168, v172, v173
	v_cvt_pk_bf16_f32 v169, v174, v175
	v_exp_f32_e32 v153, v153
	global_store_dwordx4 v[170:171], v[166:169], off offset:256 nt
	v_add_f32_e32 v138, 1.0, v138
	s_nop 0
	v_or_b32_e32 v166, 32, v152
	v_ashrrev_i32_e32 v167, 31, v166
	v_lshlrev_b64 v[170:171], 10, v[166:167]
	v_rcp_f32_e32 v166, v138
	v_add_f32_e32 v138, 1.0, v151
	v_mul_f32_e32 v151, 0xbfb8aa3b, v105
	v_rcp_f32_e32 v167, v138
	v_add_f32_e32 v138, 1.0, v153
	v_exp_f32_e32 v151, v151
	v_mul_f32_e32 v153, 0xbfb8aa3b, v98
	v_exp_f32_e32 v153, v153
	v_rcp_f32_e32 v168, v138
	v_add_f32_e32 v138, 1.0, v151
	v_rcp_f32_e32 v169, v138
	v_add_f32_e32 v138, 1.0, v153
	v_mul_f32_e32 v151, 0xbfb8aa3b, v100
	v_rcp_f32_e32 v172, v138
	v_mul_f32_e32 v138, 0xbfb8aa3b, v99
	v_exp_f32_e32 v151, v151
	v_mul_f32_e32 v153, 0xbfb8aa3b, v101
	v_exp_f32_e32 v138, v138
	v_exp_f32_e32 v153, v153
	v_add_f32_e32 v151, 1.0, v151
	v_rcp_f32_e32 v174, v151
	v_add_f32_e32 v138, 1.0, v138
	v_add_f32_e32 v151, 1.0, v153
	v_rcp_f32_e32 v175, v151
	v_rcp_f32_e32 v173, v138
	v_mul_f32_e32 v138, 0xbfb8aa3b, v78
	v_exp_f32_e32 v138, v138
	v_mul_f32_e32 v151, 0xbfb8aa3b, v79
	v_exp_f32_e32 v151, v151
	v_mul_f32_e32 v153, 0xbfb8aa3b, v80
	v_exp_f32_e32 v153, v153
	v_pk_mul_f32 v[168:169], v[104:105], v[168:169]
	v_pk_mul_f32 v[166:167], v[102:103], v[166:167]
	v_pk_mul_f32 v[174:175], v[100:101], v[174:175]
	v_pk_mul_f32 v[172:173], v[98:99], v[172:173]
	v_lshl_add_u64 v[170:171], s[8:9], 0, v[170:171]
	v_cvt_pk_bf16_f32 v166, v166, v167
	v_cvt_pk_bf16_f32 v167, v168, v169
	v_cvt_pk_bf16_f32 v168, v172, v173
	v_cvt_pk_bf16_f32 v169, v174, v175
	v_lshl_add_u64 v[170:171], v[170:171], 0, v[156:157]
	v_add_f32_e32 v138, 1.0, v138
	global_store_dwordx4 v[170:171], v[166:169], off nt
	s_nop 1
	v_rcp_f32_e32 v166, v138
	v_add_f32_e32 v138, 1.0, v151
	v_mul_f32_e32 v151, 0xbfb8aa3b, v81
	v_rcp_f32_e32 v167, v138
	v_add_f32_e32 v138, 1.0, v153
	v_exp_f32_e32 v151, v151
	v_mul_f32_e32 v153, 0xbfb8aa3b, v74
	v_exp_f32_e32 v153, v153
	v_rcp_f32_e32 v168, v138
	v_add_f32_e32 v138, 1.0, v151
	v_rcp_f32_e32 v169, v138
	v_add_f32_e32 v138, 1.0, v153
	v_mul_f32_e32 v151, 0xbfb8aa3b, v76
	v_rcp_f32_e32 v172, v138
	v_mul_f32_e32 v138, 0xbfb8aa3b, v75
	v_exp_f32_e32 v151, v151
	v_mul_f32_e32 v153, 0xbfb8aa3b, v77
	v_exp_f32_e32 v138, v138
	v_exp_f32_e32 v153, v153
	v_add_f32_e32 v151, 1.0, v151
	v_rcp_f32_e32 v174, v151
	v_add_f32_e32 v138, 1.0, v138
	v_add_f32_e32 v151, 1.0, v153
	v_rcp_f32_e32 v175, v151
	v_rcp_f32_e32 v173, v138
	v_mul_f32_e32 v138, 0xbfb8aa3b, v86
	v_exp_f32_e32 v138, v138
	v_mul_f32_e32 v151, 0xbfb8aa3b, v87
	v_pk_mul_f32 v[168:169], v[80:81], v[168:169]
	v_pk_mul_f32 v[166:167], v[78:79], v[166:167]
	v_pk_mul_f32 v[174:175], v[76:77], v[174:175]
	v_pk_mul_f32 v[172:173], v[74:75], v[172:173]
	v_exp_f32_e32 v151, v151
	v_mul_f32_e32 v153, 0xbfb8aa3b, v88
	v_cvt_pk_bf16_f32 v166, v166, v167
	v_cvt_pk_bf16_f32 v167, v168, v169
	v_cvt_pk_bf16_f32 v168, v172, v173
	v_cvt_pk_bf16_f32 v169, v174, v175
	v_exp_f32_e32 v153, v153
	global_store_dwordx4 v[170:171], v[166:169], off offset:256 nt
	v_add_f32_e32 v138, 1.0, v138
	s_nop 0
	v_or_b32_e32 v166, 48, v152
	v_ashrrev_i32_e32 v167, 31, v166
	v_lshlrev_b64 v[170:171], 10, v[166:167]
	v_rcp_f32_e32 v166, v138
	v_add_f32_e32 v138, 1.0, v151
	v_mul_f32_e32 v151, 0xbfb8aa3b, v89
	v_rcp_f32_e32 v167, v138
	v_add_f32_e32 v138, 1.0, v153
	v_exp_f32_e32 v151, v151
	v_mul_f32_e32 v153, 0xbfb8aa3b, v82
	v_exp_f32_e32 v153, v153
	v_rcp_f32_e32 v168, v138
	v_add_f32_e32 v138, 1.0, v151
	v_rcp_f32_e32 v169, v138
	v_add_f32_e32 v138, 1.0, v153
	v_mul_f32_e32 v151, 0xbfb8aa3b, v84
	v_rcp_f32_e32 v172, v138
	v_mul_f32_e32 v138, 0xbfb8aa3b, v83
	v_exp_f32_e32 v151, v151
	v_mul_f32_e32 v153, 0xbfb8aa3b, v85
	v_exp_f32_e32 v138, v138
	v_exp_f32_e32 v153, v153
	v_add_f32_e32 v151, 1.0, v151
	v_rcp_f32_e32 v174, v151
	v_add_f32_e32 v138, 1.0, v138
	v_add_f32_e32 v151, 1.0, v153
	v_rcp_f32_e32 v175, v151
	v_rcp_f32_e32 v173, v138
	v_mul_f32_e32 v138, 0xbfb8aa3b, v70
	v_exp_f32_e32 v138, v138
	v_mul_f32_e32 v151, 0xbfb8aa3b, v71
	v_exp_f32_e32 v151, v151
	v_mul_f32_e32 v153, 0xbfb8aa3b, v72
	v_exp_f32_e32 v153, v153
	v_pk_mul_f32 v[168:169], v[88:89], v[168:169]
	v_pk_mul_f32 v[166:167], v[86:87], v[166:167]
	v_pk_mul_f32 v[174:175], v[84:85], v[174:175]
	v_pk_mul_f32 v[172:173], v[82:83], v[172:173]
	v_lshl_add_u64 v[170:171], s[8:9], 0, v[170:171]
	v_cvt_pk_bf16_f32 v166, v166, v167
	v_cvt_pk_bf16_f32 v167, v168, v169
	v_cvt_pk_bf16_f32 v168, v172, v173
	v_cvt_pk_bf16_f32 v169, v174, v175
	v_lshl_add_u64 v[156:157], v[170:171], 0, v[156:157]
	v_add_f32_e32 v138, 1.0, v138
	global_store_dwordx4 v[156:157], v[166:169], off nt
	s_nop 1
	v_rcp_f32_e32 v166, v138
	v_add_f32_e32 v138, 1.0, v151
	v_mul_f32_e32 v151, 0xbfb8aa3b, v73
	v_rcp_f32_e32 v167, v138
	v_add_f32_e32 v138, 1.0, v153
	v_exp_f32_e32 v151, v151
	v_mul_f32_e32 v153, 0xbfb8aa3b, v66
	v_exp_f32_e32 v153, v153
	v_rcp_f32_e32 v168, v138
	v_add_f32_e32 v138, 1.0, v151
	v_rcp_f32_e32 v169, v138
	v_add_f32_e32 v138, 1.0, v153
	v_mul_f32_e32 v151, 0xbfb8aa3b, v68
	v_rcp_f32_e32 v170, v138
	v_mul_f32_e32 v138, 0xbfb8aa3b, v67
	v_exp_f32_e32 v151, v151
	v_mul_f32_e32 v153, 0xbfb8aa3b, v69
	v_exp_f32_e32 v138, v138
	v_exp_f32_e32 v153, v153
	v_add_f32_e32 v151, 1.0, v151
	v_rcp_f32_e32 v172, v151
	v_add_f32_e32 v138, 1.0, v138
	v_add_f32_e32 v151, 1.0, v153
	v_rcp_f32_e32 v173, v151
	v_rcp_f32_e32 v171, v138
	v_mul_f32_e32 v138, 0xbfb8aa3b, v62
	v_exp_f32_e32 v138, v138
	v_mul_f32_e32 v151, 0xbfb8aa3b, v63
	v_exp_f32_e32 v151, v151
	v_mul_f32_e32 v153, 0xbfb8aa3b, v64
	v_exp_f32_e32 v153, v153
	v_pk_mul_f32 v[168:169], v[72:73], v[168:169]
	v_pk_mul_f32 v[166:167], v[70:71], v[166:167]
	v_pk_mul_f32 v[172:173], v[68:69], v[172:173]
	v_pk_mul_f32 v[170:171], v[66:67], v[170:171]
	v_cvt_pk_bf16_f32 v166, v166, v167
	v_cvt_pk_bf16_f32 v167, v168, v169
	v_cvt_pk_bf16_f32 v168, v170, v171
	v_cvt_pk_bf16_f32 v169, v172, v173
	v_add_f32_e32 v138, 1.0, v138
	global_store_dwordx4 v[156:157], v[166:169], off offset:256 nt
	v_rcp_f32_e32 v156, v138
	v_add_f32_e32 v138, 1.0, v151
	v_mul_f32_e32 v151, 0xbfb8aa3b, v65
	v_rcp_f32_e32 v157, v138
	v_add_f32_e32 v138, 1.0, v153
	v_exp_f32_e32 v151, v151
	v_mul_f32_e32 v153, 0xbfb8aa3b, v58
	v_exp_f32_e32 v153, v153
	v_rcp_f32_e32 v166, v138
	v_add_f32_e32 v138, 1.0, v151
	v_rcp_f32_e32 v167, v138
	v_add_f32_e32 v138, 1.0, v153
	v_mul_f32_e32 v151, 0xbfb8aa3b, v60
	v_rcp_f32_e32 v168, v138
	v_mul_f32_e32 v138, 0xbfb8aa3b, v59
	v_exp_f32_e32 v151, v151
	v_mul_f32_e32 v153, 0xbfb8aa3b, v61
	v_exp_f32_e32 v138, v138
	v_exp_f32_e32 v153, v153
	v_add_f32_e32 v151, 1.0, v151
	v_rcp_f32_e32 v170, v151
	v_add_f32_e32 v138, 1.0, v138
	v_add_f32_e32 v151, 1.0, v153
	v_rcp_f32_e32 v171, v151
	v_rcp_f32_e32 v169, v138
	v_mul_f32_e32 v138, 0xbfb8aa3b, v46
	v_exp_f32_e32 v138, v138
	v_mul_f32_e32 v151, 0xbfb8aa3b, v47
	v_pk_mul_f32 v[156:157], v[62:63], v[156:157]
	v_exp_f32_e32 v151, v151
	v_mul_f32_e32 v153, 0xbfb8aa3b, v48
	v_pk_mul_f32 v[172:173], v[64:65], v[166:167]
	v_pk_mul_f32 v[170:171], v[60:61], v[170:171]
	v_pk_mul_f32 v[168:169], v[58:59], v[168:169]
	v_cvt_pk_bf16_f32 v166, v156, v157
	v_lshl_add_u64 v[156:157], v[154:155], 0, s[18:19]
	s_mov_b32 s18, 0x20000
	v_exp_f32_e32 v153, v153
	v_cvt_pk_bf16_f32 v168, v168, v169
	v_cvt_pk_bf16_f32 v169, v170, v171
	v_add_co_u32_e32 v170, vcc, s18, v154
	v_cvt_pk_bf16_f32 v167, v172, v173
	s_nop 0
	v_addc_co_u32_e32 v171, vcc, 0, v155, vcc
	v_add_f32_e32 v138, 1.0, v138
	global_store_dwordx4 v[170:171], v[166:169], off nt
	s_mov_b64 s[18:19], 0x24000
	s_nop 0
	v_rcp_f32_e32 v166, v138
	v_add_f32_e32 v138, 1.0, v151
	v_mul_f32_e32 v151, 0xbfb8aa3b, v49
	v_rcp_f32_e32 v167, v138
	v_add_f32_e32 v138, 1.0, v153
	v_exp_f32_e32 v151, v151
	v_mul_f32_e32 v153, 0xbfb8aa3b, v42
	v_exp_f32_e32 v153, v153
	v_rcp_f32_e32 v168, v138
	v_add_f32_e32 v138, 1.0, v151
	v_rcp_f32_e32 v169, v138
	v_add_f32_e32 v138, 1.0, v153
	v_mul_f32_e32 v151, 0xbfb8aa3b, v44
	v_rcp_f32_e32 v170, v138
	v_mul_f32_e32 v138, 0xbfb8aa3b, v43
	v_exp_f32_e32 v151, v151
	v_mul_f32_e32 v153, 0xbfb8aa3b, v45
	v_exp_f32_e32 v138, v138
	v_exp_f32_e32 v153, v153
	v_add_f32_e32 v151, 1.0, v151
	v_rcp_f32_e32 v172, v151
	v_add_f32_e32 v138, 1.0, v138
	v_add_f32_e32 v151, 1.0, v153
	v_rcp_f32_e32 v173, v151
	v_rcp_f32_e32 v171, v138
	v_mul_f32_e32 v138, 0xbfb8aa3b, v54
	v_exp_f32_e32 v138, v138
	v_mul_f32_e32 v151, 0xbfb8aa3b, v55
	v_exp_f32_e32 v151, v151
	v_mul_f32_e32 v153, 0xbfb8aa3b, v56
	v_exp_f32_e32 v153, v153
	v_pk_mul_f32 v[168:169], v[48:49], v[168:169]
	v_pk_mul_f32 v[166:167], v[46:47], v[166:167]
	v_pk_mul_f32 v[172:173], v[44:45], v[172:173]
	v_pk_mul_f32 v[170:171], v[42:43], v[170:171]
	v_cvt_pk_bf16_f32 v166, v166, v167
	v_cvt_pk_bf16_f32 v167, v168, v169
	v_cvt_pk_bf16_f32 v168, v170, v171
	v_cvt_pk_bf16_f32 v169, v172, v173
	v_add_f32_e32 v138, 1.0, v138
	global_store_dwordx4 v[156:157], v[166:169], off offset:256 nt
	v_rcp_f32_e32 v156, v138
	v_add_f32_e32 v138, 1.0, v151
	v_mul_f32_e32 v151, 0xbfb8aa3b, v57
	v_rcp_f32_e32 v157, v138
	v_add_f32_e32 v138, 1.0, v153
	v_exp_f32_e32 v151, v151
	v_mul_f32_e32 v153, 0xbfb8aa3b, v50
	v_exp_f32_e32 v153, v153
	v_rcp_f32_e32 v166, v138
	v_add_f32_e32 v138, 1.0, v151
	v_rcp_f32_e32 v167, v138
	v_add_f32_e32 v138, 1.0, v153
	v_mul_f32_e32 v151, 0xbfb8aa3b, v52
	v_rcp_f32_e32 v168, v138
	v_mul_f32_e32 v138, 0xbfb8aa3b, v51
	v_exp_f32_e32 v151, v151
	v_mul_f32_e32 v153, 0xbfb8aa3b, v53
	v_exp_f32_e32 v138, v138
	v_exp_f32_e32 v153, v153
	v_add_f32_e32 v151, 1.0, v151
	v_rcp_f32_e32 v170, v151
	v_add_f32_e32 v138, 1.0, v138
	v_add_f32_e32 v151, 1.0, v153
	v_rcp_f32_e32 v171, v151
	v_rcp_f32_e32 v169, v138
	v_mul_f32_e32 v138, 0xbfb8aa3b, v30
	v_exp_f32_e32 v138, v138
	v_mul_f32_e32 v151, 0xbfb8aa3b, v31
	v_pk_mul_f32 v[156:157], v[54:55], v[156:157]
	v_exp_f32_e32 v151, v151
	v_mul_f32_e32 v153, 0xbfb8aa3b, v32
	v_pk_mul_f32 v[172:173], v[56:57], v[166:167]
	v_pk_mul_f32 v[170:171], v[52:53], v[170:171]
	v_pk_mul_f32 v[168:169], v[50:51], v[168:169]
	v_cvt_pk_bf16_f32 v166, v156, v157
	v_lshl_add_u64 v[156:157], v[154:155], 0, s[18:19]
	s_mov_b32 s18, 0x24000
	v_exp_f32_e32 v153, v153
	v_cvt_pk_bf16_f32 v168, v168, v169
	v_cvt_pk_bf16_f32 v169, v170, v171
	v_add_co_u32_e32 v170, vcc, s18, v154
	v_cvt_pk_bf16_f32 v167, v172, v173
	s_nop 0
	v_addc_co_u32_e32 v171, vcc, 0, v155, vcc
	v_add_f32_e32 v138, 1.0, v138
	global_store_dwordx4 v[170:171], v[166:169], off nt
	s_mov_b64 s[18:19], 0x28000
	s_nop 0
	v_rcp_f32_e32 v166, v138
	v_add_f32_e32 v138, 1.0, v151
	v_mul_f32_e32 v151, 0xbfb8aa3b, v33
	v_rcp_f32_e32 v167, v138
	v_add_f32_e32 v138, 1.0, v153
	v_exp_f32_e32 v151, v151
	v_mul_f32_e32 v153, 0xbfb8aa3b, v26
	v_exp_f32_e32 v153, v153
	v_rcp_f32_e32 v168, v138
	v_add_f32_e32 v138, 1.0, v151
	v_rcp_f32_e32 v169, v138
	v_add_f32_e32 v138, 1.0, v153
	v_mul_f32_e32 v151, 0xbfb8aa3b, v28
	v_rcp_f32_e32 v170, v138
	v_mul_f32_e32 v138, 0xbfb8aa3b, v27
	v_exp_f32_e32 v151, v151
	v_mul_f32_e32 v153, 0xbfb8aa3b, v29
	v_exp_f32_e32 v138, v138
	v_exp_f32_e32 v153, v153
	v_add_f32_e32 v151, 1.0, v151
	v_rcp_f32_e32 v172, v151
	v_add_f32_e32 v138, 1.0, v138
	v_add_f32_e32 v151, 1.0, v153
	v_rcp_f32_e32 v173, v151
	v_rcp_f32_e32 v171, v138
	v_mul_f32_e32 v138, 0xbfb8aa3b, v38
	v_exp_f32_e32 v138, v138
	v_mul_f32_e32 v151, 0xbfb8aa3b, v39
	v_exp_f32_e32 v151, v151
	v_mul_f32_e32 v153, 0xbfb8aa3b, v40
	v_exp_f32_e32 v153, v153
	v_pk_mul_f32 v[168:169], v[32:33], v[168:169]
	v_pk_mul_f32 v[166:167], v[30:31], v[166:167]
	v_pk_mul_f32 v[172:173], v[28:29], v[172:173]
	v_pk_mul_f32 v[170:171], v[26:27], v[170:171]
	v_cvt_pk_bf16_f32 v166, v166, v167
	v_cvt_pk_bf16_f32 v167, v168, v169
	v_cvt_pk_bf16_f32 v168, v170, v171
	v_cvt_pk_bf16_f32 v169, v172, v173
	v_add_f32_e32 v138, 1.0, v138
	global_store_dwordx4 v[156:157], v[166:169], off offset:256 nt
	v_rcp_f32_e32 v156, v138
	v_add_f32_e32 v138, 1.0, v151
	v_mul_f32_e32 v151, 0xbfb8aa3b, v41
	v_rcp_f32_e32 v157, v138
	v_add_f32_e32 v138, 1.0, v153
	v_exp_f32_e32 v151, v151
	v_mul_f32_e32 v153, 0xbfb8aa3b, v34
	v_exp_f32_e32 v153, v153
	v_rcp_f32_e32 v166, v138
	v_add_f32_e32 v138, 1.0, v151
	v_rcp_f32_e32 v167, v138
	v_add_f32_e32 v138, 1.0, v153
	v_mul_f32_e32 v151, 0xbfb8aa3b, v36
	v_rcp_f32_e32 v168, v138
	v_mul_f32_e32 v138, 0xbfb8aa3b, v35
	v_exp_f32_e32 v151, v151
	v_mul_f32_e32 v153, 0xbfb8aa3b, v37
	v_exp_f32_e32 v138, v138
	v_exp_f32_e32 v153, v153
	v_add_f32_e32 v151, 1.0, v151
	v_rcp_f32_e32 v170, v151
	v_add_f32_e32 v138, 1.0, v138
	v_add_f32_e32 v151, 1.0, v153
	v_rcp_f32_e32 v171, v151
	v_rcp_f32_e32 v169, v138
	v_mul_f32_e32 v138, 0xbfb8aa3b, v14
	v_exp_f32_e32 v138, v138
	v_mul_f32_e32 v151, 0xbfb8aa3b, v15
	v_pk_mul_f32 v[156:157], v[38:39], v[156:157]
	v_exp_f32_e32 v151, v151
	v_mul_f32_e32 v153, 0xbfb8aa3b, v16
	v_pk_mul_f32 v[172:173], v[40:41], v[166:167]
	v_pk_mul_f32 v[170:171], v[36:37], v[170:171]
	v_pk_mul_f32 v[168:169], v[34:35], v[168:169]
	v_cvt_pk_bf16_f32 v166, v156, v157
	v_lshl_add_u64 v[156:157], v[154:155], 0, s[18:19]
	s_mov_b32 s18, 0x28000
	v_exp_f32_e32 v153, v153
	v_cvt_pk_bf16_f32 v168, v168, v169
	v_cvt_pk_bf16_f32 v169, v170, v171
	v_add_co_u32_e32 v170, vcc, s18, v154
	v_cvt_pk_bf16_f32 v167, v172, v173
	s_nop 0
	v_addc_co_u32_e32 v171, vcc, 0, v155, vcc
	v_add_f32_e32 v138, 1.0, v138
	global_store_dwordx4 v[170:171], v[166:169], off nt
	s_mov_b64 s[18:19], 0x2c000
	s_nop 0
	v_rcp_f32_e32 v166, v138
	v_add_f32_e32 v138, 1.0, v151
	v_mul_f32_e32 v151, 0xbfb8aa3b, v17
	v_rcp_f32_e32 v167, v138
	v_add_f32_e32 v138, 1.0, v153
	v_exp_f32_e32 v151, v151
	v_mul_f32_e32 v153, 0xbfb8aa3b, v10
	v_exp_f32_e32 v153, v153
	v_rcp_f32_e32 v168, v138
	v_add_f32_e32 v138, 1.0, v151
	v_rcp_f32_e32 v169, v138
	v_add_f32_e32 v138, 1.0, v153
	v_mul_f32_e32 v151, 0xbfb8aa3b, v12
	v_rcp_f32_e32 v170, v138
	v_mul_f32_e32 v138, 0xbfb8aa3b, v11
	v_exp_f32_e32 v151, v151
	v_mul_f32_e32 v153, 0xbfb8aa3b, v13
	v_exp_f32_e32 v138, v138
	v_exp_f32_e32 v153, v153
	v_add_f32_e32 v151, 1.0, v151
	v_rcp_f32_e32 v172, v151
	v_add_f32_e32 v138, 1.0, v138
	v_add_f32_e32 v151, 1.0, v153
	v_rcp_f32_e32 v173, v151
	v_rcp_f32_e32 v171, v138
	v_mul_f32_e32 v138, 0xbfb8aa3b, v22
	v_exp_f32_e32 v138, v138
	v_mul_f32_e32 v151, 0xbfb8aa3b, v23
	v_exp_f32_e32 v151, v151
	v_mul_f32_e32 v153, 0xbfb8aa3b, v24
	v_exp_f32_e32 v153, v153
	v_pk_mul_f32 v[168:169], v[16:17], v[168:169]
	v_pk_mul_f32 v[166:167], v[14:15], v[166:167]
	v_pk_mul_f32 v[172:173], v[12:13], v[172:173]
	v_pk_mul_f32 v[170:171], v[10:11], v[170:171]
	v_cvt_pk_bf16_f32 v166, v166, v167
	v_cvt_pk_bf16_f32 v167, v168, v169
	v_cvt_pk_bf16_f32 v168, v170, v171
	v_cvt_pk_bf16_f32 v169, v172, v173
	v_add_f32_e32 v138, 1.0, v138
	global_store_dwordx4 v[156:157], v[166:169], off offset:256 nt
	v_rcp_f32_e32 v156, v138
	v_add_f32_e32 v138, 1.0, v151
	v_mul_f32_e32 v151, 0xbfb8aa3b, v25
	v_rcp_f32_e32 v157, v138
	v_add_f32_e32 v138, 1.0, v153
	v_exp_f32_e32 v151, v151
	v_mul_f32_e32 v153, 0xbfb8aa3b, v18
	v_exp_f32_e32 v153, v153
	v_rcp_f32_e32 v166, v138
	v_add_f32_e32 v138, 1.0, v151
	v_rcp_f32_e32 v167, v138
	v_add_f32_e32 v138, 1.0, v153
	v_mul_f32_e32 v151, 0xbfb8aa3b, v20
	v_rcp_f32_e32 v168, v138
	v_mul_f32_e32 v138, 0xbfb8aa3b, v19
	v_exp_f32_e32 v151, v151
	v_mul_f32_e32 v153, 0xbfb8aa3b, v21
	v_exp_f32_e32 v138, v138
	v_exp_f32_e32 v153, v153
	v_add_f32_e32 v151, 1.0, v151
	v_rcp_f32_e32 v170, v151
	v_add_f32_e32 v138, 1.0, v138
	v_add_f32_e32 v151, 1.0, v153
	v_rcp_f32_e32 v171, v151
	v_rcp_f32_e32 v169, v138
	v_mul_f32_e32 v138, 0xbfb8aa3b, v6
	v_exp_f32_e32 v138, v138
	v_mul_f32_e32 v151, 0xbfb8aa3b, v7
	v_pk_mul_f32 v[170:171], v[20:21], v[170:171]
	v_pk_mul_f32 v[168:169], v[18:19], v[168:169]
	v_exp_f32_e32 v151, v151
	v_mul_f32_e32 v153, 0xbfb8aa3b, v8
	v_cvt_pk_bf16_f32 v168, v168, v169
	v_cvt_pk_bf16_f32 v169, v170, v171
	v_lshl_add_u64 v[170:171], v[154:155], 0, s[18:19]
	s_mov_b32 s18, 0x2c000
	v_exp_f32_e32 v153, v153
	v_pk_mul_f32 v[172:173], v[24:25], v[166:167]
	v_pk_mul_f32 v[156:157], v[22:23], v[156:157]
	v_add_co_u32_e32 v154, vcc, s18, v154
	v_cvt_pk_bf16_f32 v166, v156, v157
	v_cvt_pk_bf16_f32 v167, v172, v173
	v_addc_co_u32_e32 v155, vcc, 0, v155, vcc
	v_add_f32_e32 v138, 1.0, v138
	global_store_dwordx4 v[154:155], v[166:169], off nt
	v_rcp_f32_e32 v154, v138
	v_add_f32_e32 v138, 1.0, v151
	v_mul_f32_e32 v151, 0xbfb8aa3b, v9
	v_rcp_f32_e32 v155, v138
	v_add_f32_e32 v138, 1.0, v153
	v_exp_f32_e32 v151, v151
	v_mul_f32_e32 v153, 0xbfb8aa3b, v2
	v_exp_f32_e32 v153, v153
	v_rcp_f32_e32 v156, v138
	v_add_f32_e32 v138, 1.0, v151
	v_rcp_f32_e32 v157, v138
	v_add_f32_e32 v138, 1.0, v153
	v_mul_f32_e32 v151, 0xbfb8aa3b, v4
	v_rcp_f32_e32 v166, v138
	v_mul_f32_e32 v138, 0xbfb8aa3b, v3
	v_exp_f32_e32 v151, v151
	v_mul_f32_e32 v153, 0xbfb8aa3b, v5
	v_exp_f32_e32 v138, v138
	v_exp_f32_e32 v153, v153
	v_add_f32_e32 v151, 1.0, v151
	v_rcp_f32_e32 v168, v151
	v_add_f32_e32 v138, 1.0, v138
	v_add_f32_e32 v151, 1.0, v153
	v_rcp_f32_e32 v169, v151
	v_rcp_f32_e32 v167, v138
	v_pk_mul_f32 v[156:157], v[8:9], v[156:157]
	v_pk_mul_f32 v[154:155], v[6:7], v[154:155]
	v_pk_mul_f32 v[168:169], v[4:5], v[168:169]
	v_pk_mul_f32 v[166:167], v[2:3], v[166:167]
	v_cvt_pk_bf16_f32 v154, v154, v155
	v_cvt_pk_bf16_f32 v155, v156, v157
	v_cvt_pk_bf16_f32 v156, v166, v167
	v_cvt_pk_bf16_f32 v157, v168, v169
	global_store_dwordx4 v[170:171], v[154:157], off offset:256 nt
